# gate-up SwiGLU epilogue instruction selection: (1+e)/s^2 as one fma with the cached mean-square (re-run after a fault in the first timing attempt)
# baseline (speedup 1.0000x reference)
.LBB0_1069:
	v_lshl_add_u32 v142, s42, 8, v161
	v_or_b32_e32 v143, 16, v142
	v_or_b32_e32 v144, 32, v142
	v_or_b32_e32 v145, 48, v142
	v_add_u32_e32 v146, 0x80, v142
	v_add_u32_e32 v147, 0x90, v142
	v_add_u32_e32 v148, 0xa0, v142
	v_add_u32_e32 v149, 0xb0, v142
	s_cmp_eq_u32 s42, s98
	s_cbranch_scc1 .Lgu_scales_ready
	s_mov_b32 s98, s42
	v_mad_u64_u32 v[186:187], s[6:7], v142, 32, v[136:137]
	v_mad_u64_u32 v[188:189], s[6:7], v143, 32, v[136:137]
	v_mad_u64_u32 v[190:191], s[6:7], v144, 32, v[136:137]
	v_mad_u64_u32 v[192:193], s[6:7], v145, 32, v[136:137]
	v_mad_u64_u32 v[194:195], s[6:7], v146, 32, v[136:137]
	v_mad_u64_u32 v[196:197], s[6:7], v147, 32, v[136:137]
	v_mad_u64_u32 v[198:199], s[6:7], v148, 32, v[136:137]
	v_mad_u64_u32 v[200:201], s[6:7], v149, 32, v[136:137]
	global_load_dwordx2 v[170:171], v[186:187], off
	global_load_dwordx2 v[172:173], v[188:189], off
	global_load_dwordx2 v[174:175], v[190:191], off
	global_load_dwordx2 v[176:177], v[192:193], off
	global_load_dwordx2 v[178:179], v[194:195], off
	global_load_dwordx2 v[180:181], v[196:197], off
	global_load_dwordx2 v[182:183], v[198:199], off
	global_load_dwordx2 v[184:185], v[200:201], off
	s_waitcnt vmcnt(0)
	v_add_f32_e32 v170, v170, v171
	v_add_f32_e32 v172, v172, v173
	v_add_f32_e32 v174, v174, v175
	v_add_f32_e32 v176, v176, v177
	v_add_f32_e32 v178, v178, v179
	v_add_f32_e32 v180, v180, v181
	v_add_f32_e32 v182, v182, v183
	v_add_f32_e32 v184, v184, v185
	ds_bpermute_b32 v171, v164, v170
	ds_bpermute_b32 v173, v164, v172
	ds_bpermute_b32 v175, v164, v174
	ds_bpermute_b32 v177, v164, v176
	ds_bpermute_b32 v179, v164, v178
	ds_bpermute_b32 v181, v164, v180
	ds_bpermute_b32 v183, v164, v182
	ds_bpermute_b32 v185, v164, v184
	s_waitcnt lgkmcnt(0)
	v_add_f32_e32 v170, v170, v171
	v_add_f32_e32 v172, v172, v173
	v_add_f32_e32 v174, v174, v175
	v_add_f32_e32 v176, v176, v177
	v_add_f32_e32 v178, v178, v179
	v_add_f32_e32 v180, v180, v181
	v_add_f32_e32 v182, v182, v183
	v_add_f32_e32 v184, v184, v185
	ds_bpermute_b32 v171, v165, v170
	ds_bpermute_b32 v173, v165, v172
	ds_bpermute_b32 v175, v165, v174
	ds_bpermute_b32 v177, v165, v176
	ds_bpermute_b32 v179, v165, v178
	ds_bpermute_b32 v181, v165, v180
	ds_bpermute_b32 v183, v165, v182
	ds_bpermute_b32 v185, v165, v184
	s_waitcnt lgkmcnt(0)
	v_add_f32_e32 v170, v170, v171
	v_add_f32_e32 v172, v172, v173
	v_add_f32_e32 v174, v174, v175
	v_add_f32_e32 v176, v176, v177
	v_add_f32_e32 v178, v178, v179
	v_add_f32_e32 v180, v180, v181
	v_add_f32_e32 v182, v182, v183
	v_add_f32_e32 v184, v184, v185
	v_fmamk_f32 v170, v170, 0x3a000000, v232
	v_fmamk_f32 v172, v172, 0x3a000000, v232
	v_fmamk_f32 v174, v174, 0x3a000000, v232
	v_fmamk_f32 v176, v176, 0x3a000000, v232
	v_fmamk_f32 v178, v178, 0x3a000000, v232
	v_fmamk_f32 v180, v180, 0x3a000000, v232
	v_fmamk_f32 v182, v182, 0x3a000000, v232
	v_fmamk_f32 v184, v184, 0x3a000000, v232
	v_rsq_f32_e32 v228, v170
	v_mov_b32_e32 v229, v170
	v_rsq_f32_e32 v230, v172
	v_mov_b32_e32 v231, v172
	v_rsq_f32_e32 v238, v174
	v_mov_b32_e32 v239, v174
	v_rsq_f32_e32 v242, v176
	v_mov_b32_e32 v243, v176
	v_rsq_f32_e32 v244, v178
	v_mov_b32_e32 v245, v178
	v_rsq_f32_e32 v246, v180
	v_mov_b32_e32 v247, v180
	v_rsq_f32_e32 v248, v182
	v_mov_b32_e32 v249, v182
	v_rsq_f32_e32 v250, v184
	v_mov_b32_e32 v251, v184
	s_nop 0
.Lgu_scales_ready:
	v_lshl_or_b32 v158, s4, 7, v166
	v_ashrrev_i32_e32 v159, 31, v158
	v_lshlrev_b64 v[158:159], 1, v[158:159]
	v_mov_b64_e32 v[154:155], s[20:21]
	s_movk_i32 s6, 0x2c00
	v_mad_i64_i32 v[202:203], s[4:5], v142, s6, v[154:155]
	v_mad_i64_i32 v[204:205], s[4:5], v143, s6, v[154:155]
	v_mad_i64_i32 v[206:207], s[4:5], v144, s6, v[154:155]
	v_mad_i64_i32 v[208:209], s[4:5], v145, s6, v[154:155]
	v_mad_i64_i32 v[210:211], s[4:5], v146, s6, v[154:155]
	v_mad_i64_i32 v[212:213], s[4:5], v147, s6, v[154:155]
	v_mad_i64_i32 v[214:215], s[4:5], v148, s6, v[154:155]
	v_mad_i64_i32 v[216:217], s[4:5], v149, s6, v[154:155]
	v_lshl_add_u64 v[202:203], v[202:203], 0, v[158:159]
	v_lshl_add_u64 v[204:205], v[204:205], 0, v[158:159]
	v_lshl_add_u64 v[206:207], v[206:207], 0, v[158:159]
	v_lshl_add_u64 v[208:209], v[208:209], 0, v[158:159]
	v_lshl_add_u64 v[210:211], v[210:211], 0, v[158:159]
	v_lshl_add_u64 v[212:213], v[212:213], 0, v[158:159]
	v_lshl_add_u64 v[214:215], v[214:215], 0, v[158:159]
	v_lshl_add_u64 v[216:217], v[216:217], 0, v[158:159]
	s_mov_b64 s[42:43], -1
	s_andn2_b64 vcc, exec, s[36:37]
	v_mul_f32_e32 v152, 0xbfb8aa3b, v228
	v_pk_mul_f32 v[218:219], v[124:125], v[152:153] op_sel_hi:[1,0]
	v_pk_mul_f32 v[220:221], v[126:127], v[152:153] op_sel_hi:[1,0]
	v_pk_mul_f32 v[222:223], v[120:121], v[152:153] op_sel_hi:[1,0]
	v_pk_mul_f32 v[224:225], v[122:123], v[152:153] op_sel_hi:[1,0]
	v_exp_f32_e32 v218, v218
	v_exp_f32_e32 v219, v219
	v_exp_f32_e32 v220, v220
	v_exp_f32_e32 v221, v221
	v_exp_f32_e32 v222, v222
	v_exp_f32_e32 v223, v223
	v_exp_f32_e32 v224, v224
	v_exp_f32_e32 v225, v225
	v_fma_f32 v218, v218, v229, v229
	v_fma_f32 v219, v219, v229, v229
	v_fma_f32 v220, v220, v229, v229
	v_fma_f32 v221, v221, v229, v229
	v_fma_f32 v222, v222, v229, v229
	v_fma_f32 v223, v223, v229, v229
	v_fma_f32 v224, v224, v229, v229
	v_fma_f32 v225, v225, v229, v229
	v_rcp_f32_e32 v218, v218
	v_rcp_f32_e32 v219, v219
	v_rcp_f32_e32 v220, v220
	v_rcp_f32_e32 v221, v221
	v_rcp_f32_e32 v222, v222
	v_rcp_f32_e32 v223, v223
	v_rcp_f32_e32 v224, v224
	v_rcp_f32_e32 v225, v225
	v_pk_mul_f32 v[124:125], v[124:125], v[128:129]
	v_pk_mul_f32 v[126:127], v[126:127], v[130:131]
	v_pk_mul_f32 v[120:121], v[120:121], v[116:117]
	v_pk_mul_f32 v[122:123], v[122:123], v[118:119]
	v_pk_mul_f32 v[124:125], v[124:125], v[218:219]
	v_pk_mul_f32 v[126:127], v[126:127], v[220:221]
	v_pk_mul_f32 v[120:121], v[120:121], v[222:223]
	v_pk_mul_f32 v[122:123], v[122:123], v[224:225]
	v_cvt_pk_bf16_f32 v124, v124, v125
	v_cvt_pk_bf16_f32 v125, v126, v127
	v_cvt_pk_bf16_f32 v126, v120, v121
	v_cvt_pk_bf16_f32 v127, v122, v123
	s_waitcnt vmcnt(0)
	global_store_dwordx4 v[202:203], v[124:127], off
	v_mul_f32_e32 v152, 0xbfb8aa3b, v230
	v_pk_mul_f32 v[218:219], v[112:113], v[152:153] op_sel_hi:[1,0]
	v_pk_mul_f32 v[220:221], v[114:115], v[152:153] op_sel_hi:[1,0]
	v_pk_mul_f32 v[222:223], v[104:105], v[152:153] op_sel_hi:[1,0]
	v_pk_mul_f32 v[224:225], v[106:107], v[152:153] op_sel_hi:[1,0]
	v_exp_f32_e32 v218, v218
	v_exp_f32_e32 v219, v219
	v_exp_f32_e32 v220, v220
	v_exp_f32_e32 v221, v221
	v_exp_f32_e32 v222, v222
	v_exp_f32_e32 v223, v223
	v_exp_f32_e32 v224, v224
	v_exp_f32_e32 v225, v225
	v_fma_f32 v218, v218, v231, v231
	v_fma_f32 v219, v219, v231, v231
	v_fma_f32 v220, v220, v231, v231
	v_fma_f32 v221, v221, v231, v231
	v_fma_f32 v222, v222, v231, v231
	v_fma_f32 v223, v223, v231, v231
	v_fma_f32 v224, v224, v231, v231
	v_fma_f32 v225, v225, v231, v231
	v_rcp_f32_e32 v218, v218
	v_rcp_f32_e32 v219, v219
	v_rcp_f32_e32 v220, v220
	v_rcp_f32_e32 v221, v221
	v_rcp_f32_e32 v222, v222
	v_rcp_f32_e32 v223, v223
	v_rcp_f32_e32 v224, v224
	v_rcp_f32_e32 v225, v225
	v_pk_mul_f32 v[112:113], v[112:113], v[108:109]
	v_pk_mul_f32 v[114:115], v[114:115], v[110:111]
	v_pk_mul_f32 v[104:105], v[104:105], v[100:101]
	v_pk_mul_f32 v[106:107], v[106:107], v[102:103]
	v_pk_mul_f32 v[112:113], v[112:113], v[218:219]
	v_pk_mul_f32 v[114:115], v[114:115], v[220:221]
	v_pk_mul_f32 v[104:105], v[104:105], v[222:223]
	v_pk_mul_f32 v[106:107], v[106:107], v[224:225]
	v_cvt_pk_bf16_f32 v112, v112, v113
	v_cvt_pk_bf16_f32 v113, v114, v115
	v_cvt_pk_bf16_f32 v114, v104, v105
	v_cvt_pk_bf16_f32 v115, v106, v107
	global_store_dwordx4 v[204:205], v[112:115], off
	v_mul_f32_e32 v152, 0xbfb8aa3b, v238
	v_pk_mul_f32 v[218:219], v[96:97], v[152:153] op_sel_hi:[1,0]
	v_pk_mul_f32 v[220:221], v[98:99], v[152:153] op_sel_hi:[1,0]
	v_pk_mul_f32 v[222:223], v[88:89], v[152:153] op_sel_hi:[1,0]
	v_pk_mul_f32 v[224:225], v[90:91], v[152:153] op_sel_hi:[1,0]
	v_exp_f32_e32 v218, v218
	v_exp_f32_e32 v219, v219
	v_exp_f32_e32 v220, v220
	v_exp_f32_e32 v221, v221
	v_exp_f32_e32 v222, v222
	v_exp_f32_e32 v223, v223
	v_exp_f32_e32 v224, v224
	v_exp_f32_e32 v225, v225
	v_fma_f32 v218, v218, v239, v239
	v_fma_f32 v219, v219, v239, v239
	v_fma_f32 v220, v220, v239, v239
	v_fma_f32 v221, v221, v239, v239
	v_fma_f32 v222, v222, v239, v239
	v_fma_f32 v223, v223, v239, v239
	v_fma_f32 v224, v224, v239, v239
	v_fma_f32 v225, v225, v239, v239
	v_rcp_f32_e32 v218, v218
	v_rcp_f32_e32 v219, v219
	v_rcp_f32_e32 v220, v220
	v_rcp_f32_e32 v221, v221
	v_rcp_f32_e32 v222, v222
	v_rcp_f32_e32 v223, v223
	v_rcp_f32_e32 v224, v224
	v_rcp_f32_e32 v225, v225
	v_pk_mul_f32 v[96:97], v[96:97], v[92:93]
	v_pk_mul_f32 v[98:99], v[98:99], v[94:95]
	v_pk_mul_f32 v[88:89], v[88:89], v[84:85]
	v_pk_mul_f32 v[90:91], v[90:91], v[86:87]
	v_pk_mul_f32 v[96:97], v[96:97], v[218:219]
	v_pk_mul_f32 v[98:99], v[98:99], v[220:221]
	v_pk_mul_f32 v[88:89], v[88:89], v[222:223]
	v_pk_mul_f32 v[90:91], v[90:91], v[224:225]
	v_cvt_pk_bf16_f32 v96, v96, v97
	v_cvt_pk_bf16_f32 v97, v98, v99
	v_cvt_pk_bf16_f32 v98, v88, v89
	v_cvt_pk_bf16_f32 v99, v90, v91
	global_store_dwordx4 v[206:207], v[96:99], off
	v_mul_f32_e32 v152, 0xbfb8aa3b, v242
	v_pk_mul_f32 v[218:219], v[80:81], v[152:153] op_sel_hi:[1,0]
	v_pk_mul_f32 v[220:221], v[82:83], v[152:153] op_sel_hi:[1,0]
	v_pk_mul_f32 v[222:223], v[72:73], v[152:153] op_sel_hi:[1,0]
	v_pk_mul_f32 v[224:225], v[74:75], v[152:153] op_sel_hi:[1,0]
	v_exp_f32_e32 v218, v218
	v_exp_f32_e32 v219, v219
	v_exp_f32_e32 v220, v220
	v_exp_f32_e32 v221, v221
	v_exp_f32_e32 v222, v222
	v_exp_f32_e32 v223, v223
	v_exp_f32_e32 v224, v224
	v_exp_f32_e32 v225, v225
	v_fma_f32 v218, v218, v243, v243
	v_fma_f32 v219, v219, v243, v243
	v_fma_f32 v220, v220, v243, v243
	v_fma_f32 v221, v221, v243, v243
	v_fma_f32 v222, v222, v243, v243
	v_fma_f32 v223, v223, v243, v243
	v_fma_f32 v224, v224, v243, v243
	v_fma_f32 v225, v225, v243, v243
	v_rcp_f32_e32 v218, v218
	v_rcp_f32_e32 v219, v219
	v_rcp_f32_e32 v220, v220
	v_rcp_f32_e32 v221, v221
	v_rcp_f32_e32 v222, v222
	v_rcp_f32_e32 v223, v223
	v_rcp_f32_e32 v224, v224
	v_rcp_f32_e32 v225, v225
	v_pk_mul_f32 v[80:81], v[80:81], v[76:77]
	v_pk_mul_f32 v[82:83], v[82:83], v[78:79]
	v_pk_mul_f32 v[72:73], v[72:73], v[68:69]
	v_pk_mul_f32 v[74:75], v[74:75], v[70:71]
	v_pk_mul_f32 v[80:81], v[80:81], v[218:219]
	v_pk_mul_f32 v[82:83], v[82:83], v[220:221]
	v_pk_mul_f32 v[72:73], v[72:73], v[222:223]
	v_pk_mul_f32 v[74:75], v[74:75], v[224:225]
	v_cvt_pk_bf16_f32 v80, v80, v81
	v_cvt_pk_bf16_f32 v81, v82, v83
	v_cvt_pk_bf16_f32 v82, v72, v73
	v_cvt_pk_bf16_f32 v83, v74, v75
	global_store_dwordx4 v[208:209], v[80:83], off
	v_mul_f32_e32 v152, 0xbfb8aa3b, v244
	v_pk_mul_f32 v[218:219], v[64:65], v[152:153] op_sel_hi:[1,0]
	v_pk_mul_f32 v[220:221], v[66:67], v[152:153] op_sel_hi:[1,0]
	v_pk_mul_f32 v[222:223], v[56:57], v[152:153] op_sel_hi:[1,0]
	v_pk_mul_f32 v[224:225], v[58:59], v[152:153] op_sel_hi:[1,0]
	v_exp_f32_e32 v218, v218
	v_exp_f32_e32 v219, v219
	v_exp_f32_e32 v220, v220
	v_exp_f32_e32 v221, v221
	v_exp_f32_e32 v222, v222
	v_exp_f32_e32 v223, v223
	v_exp_f32_e32 v224, v224
	v_exp_f32_e32 v225, v225
	v_fma_f32 v218, v218, v245, v245
	v_fma_f32 v219, v219, v245, v245
	v_fma_f32 v220, v220, v245, v245
	v_fma_f32 v221, v221, v245, v245
	v_fma_f32 v222, v222, v245, v245
	v_fma_f32 v223, v223, v245, v245
	v_fma_f32 v224, v224, v245, v245
	v_fma_f32 v225, v225, v245, v245
	v_rcp_f32_e32 v218, v218
	v_rcp_f32_e32 v219, v219
	v_rcp_f32_e32 v220, v220
	v_rcp_f32_e32 v221, v221
	v_rcp_f32_e32 v222, v222
	v_rcp_f32_e32 v223, v223
	v_rcp_f32_e32 v224, v224
	v_rcp_f32_e32 v225, v225
	v_pk_mul_f32 v[64:65], v[64:65], v[60:61]
	v_pk_mul_f32 v[66:67], v[66:67], v[62:63]
	v_pk_mul_f32 v[56:57], v[56:57], v[52:53]
	v_pk_mul_f32 v[58:59], v[58:59], v[54:55]
	v_pk_mul_f32 v[64:65], v[64:65], v[218:219]
	v_pk_mul_f32 v[66:67], v[66:67], v[220:221]
	v_pk_mul_f32 v[56:57], v[56:57], v[222:223]
	v_pk_mul_f32 v[58:59], v[58:59], v[224:225]
	v_cvt_pk_bf16_f32 v64, v64, v65
	v_cvt_pk_bf16_f32 v65, v66, v67
	v_cvt_pk_bf16_f32 v66, v56, v57
	v_cvt_pk_bf16_f32 v67, v58, v59
	global_store_dwordx4 v[210:211], v[64:67], off
	v_mul_f32_e32 v152, 0xbfb8aa3b, v246
	v_pk_mul_f32 v[218:219], v[48:49], v[152:153] op_sel_hi:[1,0]
	v_pk_mul_f32 v[220:221], v[50:51], v[152:153] op_sel_hi:[1,0]
	v_pk_mul_f32 v[222:223], v[40:41], v[152:153] op_sel_hi:[1,0]
	v_pk_mul_f32 v[224:225], v[42:43], v[152:153] op_sel_hi:[1,0]
	v_exp_f32_e32 v218, v218
	v_exp_f32_e32 v219, v219
	v_exp_f32_e32 v220, v220
	v_exp_f32_e32 v221, v221
	v_exp_f32_e32 v222, v222
	v_exp_f32_e32 v223, v223
	v_exp_f32_e32 v224, v224
	v_exp_f32_e32 v225, v225
	v_fma_f32 v218, v218, v247, v247
	v_fma_f32 v219, v219, v247, v247
	v_fma_f32 v220, v220, v247, v247
	v_fma_f32 v221, v221, v247, v247
	v_fma_f32 v222, v222, v247, v247
	v_fma_f32 v223, v223, v247, v247
	v_fma_f32 v224, v224, v247, v247
	v_fma_f32 v225, v225, v247, v247
	v_rcp_f32_e32 v218, v218
	v_rcp_f32_e32 v219, v219
	v_rcp_f32_e32 v220, v220
	v_rcp_f32_e32 v221, v221
	v_rcp_f32_e32 v222, v222
	v_rcp_f32_e32 v223, v223
	v_rcp_f32_e32 v224, v224
	v_rcp_f32_e32 v225, v225
	v_pk_mul_f32 v[48:49], v[48:49], v[44:45]
	v_pk_mul_f32 v[50:51], v[50:51], v[46:47]
	v_pk_mul_f32 v[40:41], v[40:41], v[36:37]
	v_pk_mul_f32 v[42:43], v[42:43], v[38:39]
	v_pk_mul_f32 v[48:49], v[48:49], v[218:219]
	v_pk_mul_f32 v[50:51], v[50:51], v[220:221]
	v_pk_mul_f32 v[40:41], v[40:41], v[222:223]
	v_pk_mul_f32 v[42:43], v[42:43], v[224:225]
	v_cvt_pk_bf16_f32 v48, v48, v49
	v_cvt_pk_bf16_f32 v49, v50, v51
	v_cvt_pk_bf16_f32 v50, v40, v41
	v_cvt_pk_bf16_f32 v51, v42, v43
	global_store_dwordx4 v[212:213], v[48:51], off
	v_mul_f32_e32 v152, 0xbfb8aa3b, v248
	v_pk_mul_f32 v[218:219], v[32:33], v[152:153] op_sel_hi:[1,0]
	v_pk_mul_f32 v[220:221], v[34:35], v[152:153] op_sel_hi:[1,0]
	v_pk_mul_f32 v[222:223], v[24:25], v[152:153] op_sel_hi:[1,0]
	v_pk_mul_f32 v[224:225], v[26:27], v[152:153] op_sel_hi:[1,0]
	v_exp_f32_e32 v218, v218
	v_exp_f32_e32 v219, v219
	v_exp_f32_e32 v220, v220
	v_exp_f32_e32 v221, v221
	v_exp_f32_e32 v222, v222
	v_exp_f32_e32 v223, v223
	v_exp_f32_e32 v224, v224
	v_exp_f32_e32 v225, v225
	v_fma_f32 v218, v218, v249, v249
	v_fma_f32 v219, v219, v249, v249
	v_fma_f32 v220, v220, v249, v249
	v_fma_f32 v221, v221, v249, v249
	v_fma_f32 v222, v222, v249, v249
	v_fma_f32 v223, v223, v249, v249
	v_fma_f32 v224, v224, v249, v249
	v_fma_f32 v225, v225, v249, v249
	v_rcp_f32_e32 v218, v218
	v_rcp_f32_e32 v219, v219
	v_rcp_f32_e32 v220, v220
	v_rcp_f32_e32 v221, v221
	v_rcp_f32_e32 v222, v222
	v_rcp_f32_e32 v223, v223
	v_rcp_f32_e32 v224, v224
	v_rcp_f32_e32 v225, v225
	v_pk_mul_f32 v[32:33], v[32:33], v[28:29]
	v_pk_mul_f32 v[34:35], v[34:35], v[30:31]
	v_pk_mul_f32 v[24:25], v[24:25], v[20:21]
	v_pk_mul_f32 v[26:27], v[26:27], v[22:23]
	v_pk_mul_f32 v[32:33], v[32:33], v[218:219]
	v_pk_mul_f32 v[34:35], v[34:35], v[220:221]
	v_pk_mul_f32 v[24:25], v[24:25], v[222:223]
	v_pk_mul_f32 v[26:27], v[26:27], v[224:225]
	v_cvt_pk_bf16_f32 v32, v32, v33
	v_cvt_pk_bf16_f32 v33, v34, v35
	v_cvt_pk_bf16_f32 v34, v24, v25
	v_cvt_pk_bf16_f32 v35, v26, v27
	global_store_dwordx4 v[214:215], v[32:35], off
	v_mul_f32_e32 v152, 0xbfb8aa3b, v250
	v_pk_mul_f32 v[218:219], v[16:17], v[152:153] op_sel_hi:[1,0]
	v_pk_mul_f32 v[220:221], v[18:19], v[152:153] op_sel_hi:[1,0]
	v_pk_mul_f32 v[222:223], v[8:9], v[152:153] op_sel_hi:[1,0]
	v_pk_mul_f32 v[224:225], v[10:11], v[152:153] op_sel_hi:[1,0]
	v_exp_f32_e32 v218, v218
	v_exp_f32_e32 v219, v219
	v_exp_f32_e32 v220, v220
	v_exp_f32_e32 v221, v221
	v_exp_f32_e32 v222, v222
	v_exp_f32_e32 v223, v223
	v_exp_f32_e32 v224, v224
	v_exp_f32_e32 v225, v225
	v_fma_f32 v218, v218, v251, v251
	v_fma_f32 v219, v219, v251, v251
	v_fma_f32 v220, v220, v251, v251
	v_fma_f32 v221, v221, v251, v251
	v_fma_f32 v222, v222, v251, v251
	v_fma_f32 v223, v223, v251, v251
	v_fma_f32 v224, v224, v251, v251
	v_fma_f32 v225, v225, v251, v251
	v_rcp_f32_e32 v218, v218
	v_rcp_f32_e32 v219, v219
	v_rcp_f32_e32 v220, v220
	v_rcp_f32_e32 v221, v221
	v_rcp_f32_e32 v222, v222
	v_rcp_f32_e32 v223, v223
	v_rcp_f32_e32 v224, v224
	v_rcp_f32_e32 v225, v225
	v_pk_mul_f32 v[16:17], v[16:17], v[12:13]
	v_pk_mul_f32 v[18:19], v[18:19], v[14:15]
	v_pk_mul_f32 v[8:9], v[8:9], v[4:5]
	v_pk_mul_f32 v[10:11], v[10:11], v[6:7]
	v_pk_mul_f32 v[16:17], v[16:17], v[218:219]
	v_pk_mul_f32 v[18:19], v[18:19], v[220:221]
	v_pk_mul_f32 v[8:9], v[8:9], v[222:223]
	v_pk_mul_f32 v[10:11], v[10:11], v[224:225]
	v_cvt_pk_bf16_f32 v16, v16, v17
	v_cvt_pk_bf16_f32 v17, v18, v19
	v_cvt_pk_bf16_f32 v18, v8, v9
	v_cvt_pk_bf16_f32 v19, v10, v11
	global_store_dwordx4 v[216:217], v[16:19], off
	s_cbranch_vccnz .LBB0_1062
	s_andn2_b64 vcc, exec, s[2:3]
	s_cbranch_vccnz .LBB0_1061
	s_nop 0
	s_branch .LBB0_1061
